# sel_pk: hand-written unmasked selected-pair body with packed f32 softmax bias adds / scale fmas (sequential tile A then B)
# baseline (speedup 1.0000x reference)
.LBB0_1038:
	s_or_b64 exec, exec, s[0:1]
	s_bcnt1_i32_b32 s0, s21
	s_bcnt1_i32_b32 s1, s22
	s_bcnt1_i32_b32 s21, s23
	s_lshl_b32 s22, s40, 25
	s_add_u32 s22, s36, s22
	s_addc_u32 s23, s37, 0
	s_bcnt1_i32_b32 s20, s20
	s_add_i32 s0, s0, s20
	s_add_i32 s79, s0, s1
	s_add_i32 s79, s79, s21
	s_lshl_b32 s0, s29, 7
	s_add_u32 s24, s22, s0
	v_sub_co_u32_e64 v32, s[0:1], s79, 1
	s_waitcnt lgkmcnt(0)
	s_barrier
	s_addc_u32 s25, s23, 0
	s_lshl_b32 s0, s47, 20
	s_add_u32 s20, s55, s0
	s_addc_u32 s21, s56, 0
	v_add_u32_e32 v8, -2, v32
	v_max_i32_e32 v8, 0, v8
	v_add_u32_e32 v9, -3, v32
	v_max_i32_e32 v9, 0, v9
	v_lshl_add_u32 v8, v8, 2, s72
	v_lshl_add_u32 v9, v9, 2, s72
	ds_read_b32 v8, v8
	ds_read_b32 v9, v9
	s_ashr_i32 s32, s75, 2
	s_add_i32 s97, s32, -1
	s_max_i32 s97, s97, 0
	s_cmp_lt_u32 s79, 2
	s_cselect_b64 vcc, -1, 0
	v_mov_b32_e32 v139, v123
	v_mov_b32_e32 v141, v123
	v_readfirstlane_b32 s80, v32
	v_add_f32_e32 v137, v146, v146
	v_mul_f32_e32 v188, 0x40400000, v146
	v_mul_f32_e32 v189, 0x41800000, v146
	v_mul_f32_e32 v190, 0x42000000, v146
	v_mul_f32_e32 v191, 0x42400000, v146
	v_mul_f32_e32 v192, 0, v146
	v_mov_b32_e32 v234, v192
	v_mov_b32_e32 v235, v146
	v_mov_b32_e32 v238, v137
	v_mov_b32_e32 v239, v188
	s_waitcnt vmcnt(0)
	ds_write_b128 v151, v[240:243]
	ds_write2_b64 v187, v[244:245], v[246:247] offset1:2
	ds_write_b128 v151, v[248:251] offset:10240
	ds_write2_b64 v186, v[252:253], v[254:255] offset1:2
	s_lshl_b32 s98, s47, 20
	s_add_u32 s98, s57, s98
	s_addc_u32 s99, s60, 0
	s_add_i32 s29, s74, 0xfffffe01
	s_andn2_b32 s29, s29, 63
	s_cmp_gt_i32 s75, 31
	s_cselect_b32 s29, s29, 0
	s_sub_i32 s30, s74, s29
	s_ashr_i32 s30, s30, 6
	v_mov_b32_e32 v4, v138
	v_mov_b32_e32 v5, 0
	v_mov_b32_e32 v6, v140
	v_mov_b32_e32 v7, 0
	s_min_i32 s22, s30, 0
	s_lshl_b32 s22, s22, 6
	s_add_i32 s22, s22, s29
	s_ashr_i32 s23, s22, 31
	s_lshl_b64 s[100:101], s[22:23], 12
	s_add_u32 s100, s24, s100
	s_addc_u32 s101, s25, s101
	s_lshl_b64 s[22:23], s[22:23], 1
	s_add_u32 s22, s98, s22
	s_addc_u32 s23, s99, s23
	v_lshl_add_u64 v[0:1], s[100:101], 0, v[4:5]
	v_lshl_add_u64 v[2:3], s[22:23], 0, v[6:7]
	v_lshl_add_u64 v[0:1], v[0:1], 0, v[122:123]
	v_lshl_add_u64 v[2:3], v[2:3], 0, v[122:123]
	global_load_dwordx4 v[240:243], v[0:1], off offset:3072
	global_load_dwordx4 v[244:247], v[2:3], off
	s_min_i32 s22, s30, 1
	s_lshl_b32 s22, s22, 6
	s_add_i32 s22, s22, s29
	s_ashr_i32 s23, s22, 31
	s_lshl_b64 s[100:101], s[22:23], 12
	s_add_u32 s100, s24, s100
	s_addc_u32 s101, s25, s101
	s_lshl_b64 s[22:23], s[22:23], 1
	s_add_u32 s22, s98, s22
	s_addc_u32 s23, s99, s23
	v_lshl_add_u64 v[0:1], s[100:101], 0, v[4:5]
	v_lshl_add_u64 v[2:3], s[22:23], 0, v[6:7]
	v_lshl_add_u64 v[0:1], v[0:1], 0, v[122:123]
	v_lshl_add_u64 v[2:3], v[2:3], 0, v[122:123]
	global_load_dwordx4 v[248:251], v[0:1], off offset:3072
	global_load_dwordx4 v[252:255], v[2:3], off
	s_waitcnt lgkmcnt(4)
	v_readfirstlane_b32 s89, v8
	v_readfirstlane_b32 s91, v9
	s_lshl_b32 s0, s89, 6
	s_ashr_i32 s1, s0, 31
	s_lshl_b64 s[22:23], s[0:1], 12
	s_add_u32 s22, s24, s22
	s_addc_u32 s23, s25, s23
	s_lshl_b64 s[0:1], s[0:1], 1
	s_add_u32 s0, s20, s0
	s_addc_u32 s1, s21, s1
	v_lshl_add_u64 v[0:1], s[22:23], 0, v[138:139]
	v_lshl_add_u64 v[2:3], s[0:1], 0, v[140:141]
	v_lshl_add_u64 v[0:1], v[0:1], 0, v[122:123]
	v_lshl_add_u64 v[2:3], v[2:3], 0, v[122:123]
	global_load_dwordx4 v[20:23], v[0:1], off offset:2560
	global_load_dwordx4 v[16:19], v[2:3], off
	s_lshl_b32 s0, s91, 6
	s_ashr_i32 s1, s0, 31
	s_lshl_b64 s[22:23], s[0:1], 12
	s_add_u32 s22, s24, s22
	s_addc_u32 s23, s25, s23
	s_lshl_b64 s[0:1], s[0:1], 1
	s_add_u32 s0, s20, s0
	s_addc_u32 s1, s21, s1
	v_lshl_add_u64 v[4:5], s[22:23], 0, v[138:139]
	v_lshl_add_u64 v[6:7], s[0:1], 0, v[140:141]
	v_lshl_add_u64 v[4:5], v[4:5], 0, v[122:123]
	v_lshl_add_u64 v[6:7], v[6:7], 0, v[122:123]
	global_load_dwordx4 v[28:31], v[4:5], off offset:2560
	global_load_dwordx4 v[24:27], v[6:7], off
	s_waitcnt lgkmcnt(0)
	s_barrier
	v_lshl_add_u64 v[0:1], s[24:25], 0, v[138:139]
	v_lshl_add_u64 v[120:121], v[0:1], 0, v[122:123]
	s_and_b64 vcc, exec, vcc
	s_cbranch_vccnz .LBB0_1050
	v_lshl_add_u64 v[0:1], s[20:21], 0, v[140:141]
	v_mov_b32_e32 v36, 0
	v_lshl_add_u64 v[148:149], v[0:1], 0, v[122:123]
	v_sub_u32_e32 v139, v144, v124
	v_mov_b32_e32 v32, v123
	v_mov_b32_e32 v33, v123
	v_mov_b32_e32 v34, v123
	v_mov_b32_e32 v35, v123
	s_mov_b32 s83, 5
	s_movk_i32 s81, 0x80
	s_mov_b32 s82, s72
	v_mov_b32_e32 v37, v36
	v_mov_b32_e32 v38, v36
	v_mov_b32_e32 v39, v36
	v_mov_b32_e32 v40, v36
	v_mov_b32_e32 v41, v36
	v_mov_b32_e32 v42, v36
	v_mov_b32_e32 v43, v36
	v_mov_b32_e32 v44, v36
	v_mov_b32_e32 v45, v36
	v_mov_b32_e32 v46, v36
	v_mov_b32_e32 v47, v36
	v_mov_b32_e32 v84, v36
	v_mov_b32_e32 v85, v36
	v_mov_b32_e32 v86, v36
	v_mov_b32_e32 v87, v36

.LBB0_1046:
	s_andn2_b64 vcc, exec, s[22:23]
	s_cbranch_vccnz .LBB0_1048
	s_mov_b32 s30, 0x3e38aa3b
	s_mov_b32 s31, 0x3e38aa3b
	s_mov_b32 s29, s28
	s_sub_i32 s22, s81, 64
	s_and_b32 s22, s22, 0xc0
	s_mulk_i32 s22, 0xa0
	v_add_u32_e32 v193, s22, v153
	s_waitcnt lgkmcnt(7)
	v_mfma_f32_16x16x32_bf16 v[0:3], v[88:91], v[60:63], 0
	s_waitcnt lgkmcnt(5)
	v_mfma_f32_16x16x32_bf16 v[4:7], v[96:99], v[60:63], 0
	s_waitcnt lgkmcnt(3)
	v_mfma_f32_16x16x32_bf16 v[8:11], v[104:107], v[60:63], 0
	s_waitcnt lgkmcnt(1)
	v_mfma_f32_16x16x32_bf16 v[12:15], v[112:115], v[60:63], 0
	v_mfma_f32_16x16x32_bf16 v[0:3], v[92:95], v[56:59], v[0:3]
	v_mfma_f32_16x16x32_bf16 v[4:7], v[100:103], v[56:59], v[4:7]
	v_mfma_f32_16x16x32_bf16 v[8:11], v[108:111], v[56:59], v[8:11]
	s_waitcnt lgkmcnt(0)
	v_mfma_f32_16x16x32_bf16 v[12:15], v[116:119], v[56:59], v[12:15]
	s_setprio 0
	ds_read_b128 v[88:91], v143 offset:40960
	ds_read_b128 v[92:95], v143 offset:43520
	ds_read_b128 v[96:99], v143 offset:46080
	ds_read_b128 v[100:103], v143 offset:48640
	ds_read_b128 v[104:107], v143 offset:41024
	ds_read_b128 v[108:111], v143 offset:43584
	ds_read_b128 v[112:115], v143 offset:46144
	ds_read_b128 v[116:119], v143 offset:48704
	ds_read_b128 v[194:197], v193
	ds_read_b128 v[198:201], v193 offset:64
	ds_read_b128 v[202:205], v193 offset:2560
	ds_read_b128 v[206:209], v193 offset:2624
	ds_read_b128 v[210:213], v193 offset:5120
	ds_read_b128 v[214:217], v193 offset:5184
	ds_read_b128 v[218:221], v193 offset:7680
	v_mul_f32_e64 v226, -v146, v147
	v_cndmask_b32_e64 v226, v179, v226, s[20:21]
	v_add_f32_e32 v228, v192, v226
	v_pk_add_f32 v[230:231], v[228:229], v[234:235] op_sel_hi:[0,1]
	v_pk_add_f32 v[232:233], v[228:229], v[238:239] op_sel_hi:[0,1]
	v_pk_fma_f32 v[0:1], v[0:1], s[30:31], v[230:231]
	v_pk_fma_f32 v[2:3], v[2:3], s[30:31], v[232:233]
	v_exp_f32_e32 v0, v0
	v_exp_f32_e32 v1, v1
	v_exp_f32_e32 v2, v2
	v_exp_f32_e32 v3, v3
	v_add_f32_e32 v228, v189, v226
	v_pk_add_f32 v[230:231], v[228:229], v[234:235] op_sel_hi:[0,1]
	v_pk_add_f32 v[232:233], v[228:229], v[238:239] op_sel_hi:[0,1]
	v_pk_fma_f32 v[4:5], v[4:5], s[30:31], v[230:231]
	v_pk_fma_f32 v[6:7], v[6:7], s[30:31], v[232:233]
	v_exp_f32_e32 v4, v4
	v_exp_f32_e32 v5, v5
	v_exp_f32_e32 v6, v6
	v_exp_f32_e32 v7, v7
	v_add_f32_e32 v228, v190, v226
	v_pk_add_f32 v[230:231], v[228:229], v[234:235] op_sel_hi:[0,1]
	v_pk_add_f32 v[232:233], v[228:229], v[238:239] op_sel_hi:[0,1]
	v_pk_fma_f32 v[8:9], v[8:9], s[30:31], v[230:231]
	v_pk_fma_f32 v[10:11], v[10:11], s[30:31], v[232:233]
	v_exp_f32_e32 v8, v8
	v_exp_f32_e32 v9, v9
	v_exp_f32_e32 v10, v10
	v_exp_f32_e32 v11, v11
	v_add_f32_e32 v228, v191, v226
	v_pk_add_f32 v[230:231], v[228:229], v[234:235] op_sel_hi:[0,1]
	v_pk_add_f32 v[232:233], v[228:229], v[238:239] op_sel_hi:[0,1]
	v_pk_fma_f32 v[12:13], v[12:13], s[30:31], v[230:231]
	v_pk_fma_f32 v[14:15], v[14:15], s[30:31], v[232:233]
	v_exp_f32_e32 v12, v12
	v_exp_f32_e32 v13, v13
	v_exp_f32_e32 v14, v14
	v_exp_f32_e32 v15, v15
	v_cvt_pk_bf16_f32 v226, v0, v1
	v_cvt_pk_bf16_f32 v227, v2, v3
	v_cvt_pk_bf16_f32 v228, v4, v5
	v_cvt_pk_bf16_f32 v229, v6, v7
	v_cvt_pk_bf16_f32 v230, v8, v9
	v_cvt_pk_bf16_f32 v231, v10, v11
	v_cvt_pk_bf16_f32 v232, v12, v13
	v_cvt_pk_bf16_f32 v233, v14, v15
	s_nop 1
	s_setprio 1
	s_waitcnt lgkmcnt(14)
	v_mfma_f32_16x16x32_bf16 v[0:3], v[88:91], v[226:229], v[36:39]
	ds_read_b128 v[222:225], v193 offset:7744
	s_waitcnt lgkmcnt(14)
	v_mfma_f32_16x16x32_bf16 v[4:7], v[92:95], v[226:229], v[40:43]
	s_waitcnt lgkmcnt(13)
	v_mfma_f32_16x16x32_bf16 v[8:11], v[96:99], v[226:229], v[44:47]
	s_waitcnt lgkmcnt(12)
	v_mfma_f32_16x16x32_bf16 v[12:15], v[100:103], v[226:229], v[84:87]
	v_pk_mov_b32 v[36:37], s[28:29], s[28:29] op_sel:[0,1]
	v_pk_mov_b32 v[38:39], s[28:29], s[28:29] op_sel:[0,1]
	s_nop 1
	v_mfma_f32_16x16x32_bf16 v[80:83], v[36:39], v[226:229], v[32:35]
	s_waitcnt lgkmcnt(11)
	v_mfma_f32_16x16x32_bf16 v[0:3], v[104:107], v[230:233], v[0:3]
	s_waitcnt lgkmcnt(10)
	v_mfma_f32_16x16x32_bf16 v[4:7], v[108:111], v[230:233], v[4:7]
	s_waitcnt lgkmcnt(9)
	v_mfma_f32_16x16x32_bf16 v[8:11], v[112:115], v[230:233], v[8:11]
	s_waitcnt lgkmcnt(8)
	v_mfma_f32_16x16x32_bf16 v[12:15], v[116:119], v[230:233], v[12:15]
	v_mfma_f32_16x16x32_bf16 v[80:83], v[36:39], v[230:233], v[80:83]
	s_waitcnt lgkmcnt(7)
	v_mfma_f32_16x16x32_bf16 v[36:39], v[194:197], v[60:63], 0
	s_waitcnt lgkmcnt(5)
	v_mfma_f32_16x16x32_bf16 v[40:43], v[202:205], v[60:63], 0
	s_waitcnt lgkmcnt(3)
	v_mfma_f32_16x16x32_bf16 v[44:47], v[210:213], v[60:63], 0
	s_waitcnt lgkmcnt(1)
	v_mfma_f32_16x16x32_bf16 v[84:87], v[218:221], v[60:63], 0
	v_mfma_f32_16x16x32_bf16 v[36:39], v[198:201], v[56:59], v[36:39]
	v_mfma_f32_16x16x32_bf16 v[40:43], v[206:209], v[56:59], v[40:43]
	v_mfma_f32_16x16x32_bf16 v[44:47], v[214:217], v[56:59], v[44:47]
	s_waitcnt lgkmcnt(0)
	v_mfma_f32_16x16x32_bf16 v[84:87], v[222:225], v[56:59], v[84:87]
	s_setprio 0
	ds_read_b128 v[194:197], v193 offset:40960
	ds_read_b128 v[198:201], v193 offset:43520
	ds_read_b128 v[202:205], v193 offset:46080
	ds_read_b128 v[206:209], v193 offset:48640
	ds_read_b128 v[210:213], v193 offset:41024
	ds_read_b128 v[214:217], v193 offset:43584
	ds_read_b128 v[218:221], v193 offset:46144
	ds_read_b128 v[222:225], v193 offset:48704
	v_mul_f32_e64 v226, -v146, v141
	v_cndmask_b32_e64 v226, v179, v226, s[0:1]
	v_add_f32_e32 v228, v192, v226
	v_pk_add_f32 v[230:231], v[228:229], v[234:235] op_sel_hi:[0,1]
	v_pk_add_f32 v[232:233], v[228:229], v[238:239] op_sel_hi:[0,1]
	v_pk_fma_f32 v[36:37], v[36:37], s[30:31], v[230:231]
	v_pk_fma_f32 v[38:39], v[38:39], s[30:31], v[232:233]
	v_exp_f32_e32 v36, v36
	v_exp_f32_e32 v37, v37
	v_exp_f32_e32 v38, v38
	v_exp_f32_e32 v39, v39
	v_add_f32_e32 v228, v189, v226
	v_pk_add_f32 v[230:231], v[228:229], v[234:235] op_sel_hi:[0,1]
	v_pk_add_f32 v[232:233], v[228:229], v[238:239] op_sel_hi:[0,1]
	v_pk_fma_f32 v[40:41], v[40:41], s[30:31], v[230:231]
	v_pk_fma_f32 v[42:43], v[42:43], s[30:31], v[232:233]
	v_exp_f32_e32 v40, v40
	v_exp_f32_e32 v41, v41
	v_exp_f32_e32 v42, v42
	v_exp_f32_e32 v43, v43
	v_add_f32_e32 v228, v190, v226
	v_pk_add_f32 v[230:231], v[228:229], v[234:235] op_sel_hi:[0,1]
	v_pk_add_f32 v[232:233], v[228:229], v[238:239] op_sel_hi:[0,1]
	v_pk_fma_f32 v[44:45], v[44:45], s[30:31], v[230:231]
	v_pk_fma_f32 v[46:47], v[46:47], s[30:31], v[232:233]
	v_exp_f32_e32 v44, v44
	v_exp_f32_e32 v45, v45
	v_exp_f32_e32 v46, v46
	v_exp_f32_e32 v47, v47
	v_add_f32_e32 v228, v191, v226
	v_pk_add_f32 v[230:231], v[228:229], v[234:235] op_sel_hi:[0,1]
	v_pk_add_f32 v[232:233], v[228:229], v[238:239] op_sel_hi:[0,1]
	v_pk_fma_f32 v[84:85], v[84:85], s[30:31], v[230:231]
	v_pk_fma_f32 v[86:87], v[86:87], s[30:31], v[232:233]
	v_exp_f32_e32 v84, v84
	v_exp_f32_e32 v85, v85
	v_exp_f32_e32 v86, v86
	v_exp_f32_e32 v87, v87
	v_cvt_pk_bf16_f32 v88, v36, v37
	v_cvt_pk_bf16_f32 v89, v38, v39
	v_cvt_pk_bf16_f32 v90, v40, v41
	v_cvt_pk_bf16_f32 v91, v42, v43
	v_cvt_pk_bf16_f32 v92, v44, v45
	v_cvt_pk_bf16_f32 v93, v46, v47
	v_cvt_pk_bf16_f32 v94, v84, v85
	v_cvt_pk_bf16_f32 v95, v86, v87
	v_pk_mov_b32 v[96:97], s[28:29], s[28:29] op_sel:[0,1]
	v_pk_mov_b32 v[98:99], s[28:29], s[28:29] op_sel:[0,1]
	s_nop 1
	s_setprio 1
	s_waitcnt lgkmcnt(7)
	v_mfma_f32_16x16x32_bf16 v[0:3], v[194:197], v[88:91], v[0:3]
	s_waitcnt lgkmcnt(6)
	v_mfma_f32_16x16x32_bf16 v[4:7], v[198:201], v[88:91], v[4:7]
	s_waitcnt lgkmcnt(5)
	v_mfma_f32_16x16x32_bf16 v[8:11], v[202:205], v[88:91], v[8:11]
	s_waitcnt lgkmcnt(4)
	v_mfma_f32_16x16x32_bf16 v[12:15], v[206:209], v[88:91], v[12:15]
	v_mfma_f32_16x16x32_bf16 v[80:83], v[96:99], v[88:91], v[80:83]
	s_waitcnt lgkmcnt(3)
	v_mfma_f32_16x16x32_bf16 v[0:3], v[210:213], v[92:95], v[0:3]
	s_waitcnt lgkmcnt(2)
	v_mfma_f32_16x16x32_bf16 v[4:7], v[214:217], v[92:95], v[4:7]
	s_waitcnt lgkmcnt(1)
	v_mfma_f32_16x16x32_bf16 v[8:11], v[218:221], v[92:95], v[8:11]
	s_waitcnt lgkmcnt(0)
	v_mfma_f32_16x16x32_bf16 v[12:15], v[222:225], v[92:95], v[12:15]
	v_mfma_f32_16x16x32_bf16 v[80:83], v[96:99], v[92:95], v[80:83]
